# attention: PV MFMAs before the tile barrier interleaved with row-max chain; K/V fragment prefetch across barrier
# speedup vs baseline: 1.0025x; 1.0025x over previous
; #define LAS __attribute__((address_space(3)))
; __device__ __forceinline__ v8i ld32(const LAS char* a0, const LAS char* a1) { const v4i x = *(const LAS v4i*)a0, y = *(const LAS v4i*)a1; return (v8i){x[0], x[1], x[2], x[3], y[0], y[1], y[2], y[3]}; }
; #define MFMA8QK(A, B, C) __builtin_amdgcn_mfma_scale_f32_32x32x64_f8f6f4(A, B, C, 0, 0, 0, 0x7F7F7F7F, 0, 0x7C7C7C7C)
; #define WBAR() do { asm volatile("s_waitcnt vmcnt(0) lgkmcnt(0)" ::: "memory"); __builtin_amdgcn_s_barrier(); asm volatile("" ::: "memory"); } while (0)
; __device__ __forceinline__ void qkt(f32x16& p0, f32x16& p1, const LAS char* Ks, int ka0, int ka1, const v8i* qf, const f32x16& negm) {
; #pragma unroll
;     for (int st = 0; st < 3; ++st) {
;         const v8i k0 = ld32(Ks + ka0 + 64 * st, Ks + ka1 + 64 * st), k1 = ld32(Ks + ka0 + 64 * st + 32 * 192, Ks + ka1 + 64 * st + 32 * 192);
;         if (st == 0) { p0 = MFMA8QK(k0, qf[st], negm); p1 = MFMA8QK(k1, qf[st], negm); }
;         else { p0 = MFMA8QK(k0, qf[st], p0); p1 = MFMA8QK(k1, qf[st], p1); } }
; __device__ __forceinline__ void attn_unit(const unsigned char* __restrict__ Qb, const unsigned char* __restrict__ Kh, const unsigned char* __restrict__ VTh, f16* __restrict__ Ob, int seq, LAS char* lds) {
;     ...
;     const int sw = (r32 >> 2) & 3;
;     const int ka0 = r32 * 192 + (((2 * hi) ^ sw) << 4), ka1 = r32 * 192 + (((2 * hi + 1) ^ sw) << 4);
;     const int va0 = r32 * 64 + (((2 * hi) ^ sw) << 4), va1 = r32 * 64 + (((2 * hi + 1) ^ sw) << 4);
;     ...
;     f32x16 pA0, pA1, pB0, pB1; float dlA, dlB, alA, alB; v8i pa; const int NT = seq / 64;
;     const int NS = NT >> 1;
;     WBAR();
;     ISSUE(0);
;     WBAR();
;     if (1 < NS) ISSUE(1);
;     qkt(pA0, pA1, KSL(0), ka0, ka1, qf, negm); partialSM<true>(pA0, pA1, negm, dlA, alA);
.LBB0_586:
	v_lshrrev_b32_e32 v0, 2, v2
	v_bfe_u32 v2, v2, 2, 2
	v_lshlrev_b32_e32 v3, 1, v239
	v_bitop3_b32 v0, v3, v0, 3 bitop3:0x78
	v_bitop3_b32 v2, v3, v2, 1 bitop3:0x36
	v_lshlrev_b32_e32 v0, 4, v0
	v_lshlrev_b32_e32 v58, 4, v2
	v_mul_u32_u24_e32 v2, 0xc0, v238
	v_or_b32_e32 v244, v0, v2
	s_add_i32 m0, s15, 0
	v_or_b32_e32 v245, v58, v2
	global_load_lds_dwordx4 v4, s[0:1]
	v_add_u32_e32 v59, 0, v244
	v_add_u32_e32 v60, 0, v245
	ds_read_b128 v[2:5], v59 offset:49152
	ds_read_b128 v[6:9], v60 offset:49152
	v_readlane_b32 s68, v253, 62
	v_readlane_b32 s69, v253, 63
	v_readlane_b32 s70, v254, 0
	v_readlane_b32 s71, v254, 1
	v_readlane_b32 s72, v254, 2
	v_readlane_b32 s73, v254, 3
	v_readlane_b32 s74, v254, 4
	v_readlane_b32 s75, v254, 5
	v_readlane_b32 s76, v254, 6
	v_readlane_b32 s77, v254, 7
	v_readlane_b32 s78, v254, 8
	v_readlane_b32 s79, v254, 9
	v_readlane_b32 s80, v254, 10
	v_readlane_b32 s81, v254, 11
	v_readlane_b32 s82, v254, 12
	v_readlane_b32 s83, v254, 13
	s_mov_b32 s69, s68
	s_mov_b32 s70, s68
	s_mov_b32 s71, s68
	s_mov_b32 s72, s68
	s_mov_b32 s73, s68
	s_mov_b32 s74, s68
	s_mov_b32 s75, s68
	s_mov_b32 s76, s68
	s_mov_b32 s77, s68
	s_mov_b32 s78, s68
	s_mov_b32 s79, s68
	s_mov_b32 s80, s68
	s_mov_b32 s81, s68
	s_mov_b32 s82, s68
	s_mov_b32 s83, s68
	v_mov_b64_e32 v[18:19], s[68:69]
	v_mov_b64_e32 v[20:21], s[70:71]
	v_mov_b64_e32 v[22:23], s[72:73]
	v_mov_b64_e32 v[24:25], s[74:75]
	v_mov_b64_e32 v[26:27], s[76:77]
	v_mov_b64_e32 v[28:29], s[78:79]
	v_mov_b64_e32 v[30:31], s[80:81]
	v_mov_b64_e32 v[32:33], s[82:83]
	ds_read_b128 v[34:37], v59 offset:49216
	ds_read_b128 v[38:41], v60 offset:49216
	s_waitcnt vmcnt(0) lgkmcnt(0)
	v_mfma_scale_f32_32x32x64_f8f6f4 v[2:17], v[2:9], v[184:191], v[18:33], v234, v233 op_sel_hi:[0,0,0]
	ds_read_b128 v[46:49], v60 offset:55296
	ds_read_b128 v[42:45], v59 offset:55296
	ds_read_b128 v[50:53], v59 offset:49280
	ds_read_b128 v[54:57], v60 offset:49280
	s_mov_b32 s0, s68
	v_writelane_b32 v253, s0, 62
	s_lshl_b32 s28, s2, 13
	s_add_i32 s28, s28, s17
	v_writelane_b32 v254, s2, 0
	v_writelane_b32 v254, s3, 1
	v_writelane_b32 v254, s4, 2
	v_writelane_b32 v254, s5, 3
	v_writelane_b32 v254, s6, 4
	v_writelane_b32 v254, s7, 5
	v_writelane_b32 v254, s8, 6
	v_writelane_b32 v254, s9, 7
	v_writelane_b32 v254, s10, 8
	v_writelane_b32 v254, s11, 9
	s_waitcnt lgkmcnt(2)
	v_mfma_scale_f32_32x32x64_f8f6f4 v[18:33], v[42:49], v[184:191], v[18:33], v234, v233 op_sel_hi:[0,0,0]
	v_writelane_b32 v254, s12, 10
	v_writelane_b32 v254, s13, 11
	v_writelane_b32 v254, s14, 12
	v_writelane_b32 v254, s15, 13
	s_and_b32 s0, s14, 0x3fffffc0
	s_lshl_b32 s0, s0, 2
	s_add_i32 s20, s0, 0
	s_lshl_b32 s0, s2, 12
	s_lshl_b32 s35, s16, 13
	s_add_i32 s29, s28, s0
	s_add_i32 s35, s35, s19
	s_lshl_b32 s0, s16, 12
	s_lshl_b32 s26, s18, 13
	s_lshl_b32 s22, s2, 6
	s_add_i32 s2, s35, s0
	v_mfma_scale_f32_32x32x64_f8f6f4 v[2:17], v[34:41], v[176:183], v[2:17], v234, v233 op_sel_hi:[0,0,0]
	ds_read_b128 v[38:41], v60 offset:55360
	ds_read_b128 v[34:37], v59 offset:55360
	ds_read_b128 v[42:45], v59 offset:55424
	ds_read_b128 v[46:49], v60 offset:55424
	s_add_i32 s26, s26, s46
	s_lshl_b32 s0, s18, 12
	s_lshl_b32 s31, s33, 13
	s_add_i32 s20, s20, 0x18000
	s_add_i32 s27, s26, s0
	s_add_i32 s31, s31, s50
	s_lshl_b32 s0, s33, 12
	v_or_b32_e32 v246, 0x3800, v58
	v_or_b32_e32 v248, 0x3000, v58
	v_or_b32_e32 v249, 0x2800, v58
	v_or_b32_e32 v250, 0x2000, v58
	v_or_b32_e32 v251, 0x3800, v0
	v_or_b32_e32 v252, 0x3000, v0
	v_or_b32_e32 v231, 0x2800, v0
	s_waitcnt lgkmcnt(2)
	v_mfma_scale_f32_32x32x64_f8f6f4 v[18:33], v[34:41], v[176:183], v[18:33], v234, v233 op_sel_hi:[0,0,0]
	v_lshlrev_b32_e32 v34, 6, v238
	v_or_b32_e32 v240, v58, v34
	v_or_b32_e32 v241, v0, v34
	v_add_u32_e32 v247, 0, v34
	v_or_b32_e32 v218, 0x2000, v0
	v_mov_b32_e32 v0, v1
	v_writelane_b32 v253, s1, 63
	s_mov_b32 s21, 2
	s_lshr_b32 s47, s3, 6
	s_lshr_b32 s14, s3, 7
	s_mov_b32 s15, 0
	v_cmp_eq_u32_e64 s[12:13], 0, v239
	v_lshl_add_u32 v243, v238, 2, s20
	v_lshlrev_b32_e32 v242, 4, v239
	s_lshl_b32 s34, s16, 6
	v_mfma_scale_f32_32x32x64_f8f6f4 v[2:17], v[50:57], v[168:175], v[2:17], v234, v233 op_sel_hi:[0,0,0]
	s_lshl_b32 s3, s18, 6
	s_lshl_b32 s30, s33, 6
	s_add_i32 s49, s31, s0
	s_lshl_b32 s16, s42, 6
	s_add_i32 s18, s38, s51
	s_add_i32 s33, s39, s51
	s_mov_b32 s68, 0xfffe5000
	s_mov_b32 s69, 0xfffe6000
	s_mov_b32 s70, 0xfffe7000
	s_mov_b32 s71, 0xfffe8000
	s_mov_b32 s72, 0xfffe9000
	s_mov_b32 s73, 0xfffea000
	s_mov_b32 s74, 0xfffeb000
	s_mov_b32 s75, 0xfffec000
	s_mov_b32 s76, 0xfffed000
	s_waitcnt lgkmcnt(0)
; #define WBAR() do { asm volatile("s_waitcnt vmcnt(0) lgkmcnt(0)" ::: "memory"); __builtin_amdgcn_s_barrier(); asm volatile("" ::: "memory"); } while (0)
; template <bool FIRST>
; __device__ __forceinline__ void partialSM(f32x16& p0, f32x16& p1, f32x16& negm, float& dl, float& alpha) {
;     float pmax = p0[0];
; #pragma unroll
;     for (int r = 1; r < 16; ++r) pmax = fmaxf(pmax, p0[r]);
; #pragma unroll
;     for (int r = 0; r < 16; ++r) pmax = fmaxf(pmax, p1[r]);
;     { auto rr = __builtin_amdgcn_permlane32_swap(__float_as_uint(pmax), __float_as_uint(pmax), false, false);
;       pmax = fmaxf(__uint_as_float(rr[0]), __uint_as_float(rr[1])); }
;     if (FIRST) {
;         dl = 0.f; alpha = 1.f; const float d0_ = pmax - SH;
; #pragma unroll
;         for (int r = 0; r < 16; ++r) { p0[r] -= d0_; p1[r] -= d0_; negm[r] -= d0_; }
;     } else {
;         const bool keep = __all(pmax <= SH + THRL);
;         dl = keep ? 0.f : fmaxf(pmax - SH, 0.f); alpha = __builtin_amdgcn_exp2f(-dl);
;     }
; #pragma unroll
;     for (int r = 0; r < 16; ++r) p0[r] = __builtin_amdgcn_exp2f(p0[r]);
; }
; __device__ __forceinline__ void attn_unit(const unsigned char* __restrict__ Qb, const unsigned char* __restrict__ Kh, const unsigned char* __restrict__ VTh, f16* __restrict__ Ob, int seq, LAS char* lds) {
;     ...
;     f32x16 pA0, pA1, pB0, pB1; float dlA, dlB, alA, alB; v8i pa; const int NT = seq / 64;
;     const int NS = NT >> 1;
;     WBAR();
;     ISSUE(0);
;     WBAR();
;     if (1 < NS) ISSUE(1);
	v_mfma_scale_f32_32x32x64_f8f6f4 v[18:33], v[42:49], v[168:175], v[18:33], v234, v233 op_sel_hi:[0,0,0]
	s_nop 2
	v_max_f32_e32 v35, v3, v3
	v_max_f32_e32 v36, v2, v2
	v_max_f32_e32 v35, v36, v35
	v_max3_f32 v35, v35, v4, v5
	v_max3_f32 v35, v35, v6, v7
	v_max3_f32 v35, v35, v8, v9
	v_max3_f32 v35, v35, v10, v11
	v_max3_f32 v35, v35, v12, v13
	v_max3_f32 v35, v35, v14, v15
	v_max3_f32 v35, v35, v16, v17
	s_mov_b32 s77, 0xfffee000
	s_mov_b32 s78, 0xfffef000
	s_mov_b32 s79, 0xffff0000
	s_mov_b32 s80, 0xffff1000
	s_mov_b32 s81, 0xffff2000
	s_nop 1
	v_max3_f32 v35, v35, v18, v19
	v_max3_f32 v35, v35, v20, v21
	v_max3_f32 v35, v35, v22, v23
	v_max3_f32 v35, v35, v24, v25
	v_max3_f32 v35, v35, v26, v27
	v_max3_f32 v35, v35, v28, v29
	v_max3_f32 v35, v35, v30, v31
	v_max3_f32 v35, v35, v32, v33
	v_mov_b32_e32 v36, v35
	s_nop 1
	v_permlane32_swap_b32_e32 v35, v36
	v_max_f32_e32 v36, v36, v36
	v_max_f32_e32 v35, v35, v35
	v_max_f32_e32 v35, v35, v36
	v_add_f32_e32 v35, -4.0, v35
	v_sub_f32_e32 v2, v2, v35
	v_exp_f32_e32 v228, v2
	v_sub_f32_e32 v2, v3, v35
	v_exp_f32_e32 v229, v2
	v_sub_f32_e32 v2, v4, v35
	v_exp_f32_e32 v220, v2
	v_sub_f32_e32 v2, v5, v35
	v_exp_f32_e32 v221, v2
	v_sub_f32_e32 v2, v6, v35
	v_exp_f32_e32 v226, v2
	v_sub_f32_e32 v2, v7, v35
	v_exp_f32_e32 v227, v2
	v_sub_f32_e32 v2, v8, v35
	v_exp_f32_e32 v224, v2
	v_sub_f32_e32 v2, v9, v35
	v_exp_f32_e32 v225, v2
	v_sub_f32_e32 v2, v10, v35
	v_exp_f32_e32 v222, v2
	v_sub_f32_e32 v2, v11, v35
	v_exp_f32_e32 v223, v2
	v_sub_f32_e32 v2, v12, v35
	v_exp_f32_e32 v162, v2
	v_sub_f32_e32 v2, v13, v35
	v_exp_f32_e32 v163, v2
	v_sub_f32_e32 v2, v14, v35
	v_exp_f32_e32 v166, v2
	v_sub_f32_e32 v2, v15, v35
	v_exp_f32_e32 v167, v2
	v_sub_f32_e32 v2, v16, v35
	v_exp_f32_e32 v164, v2
	v_sub_f32_e32 v2, v17, v35
	v_exp_f32_e32 v165, v2
	v_mov_b32_e32 v14, v1
	v_mov_b32_e32 v15, v1
	v_sub_f32_e32 v127, v33, v35
	v_sub_f32_e32 v126, v32, v35
	v_sub_f32_e32 v125, v31, v35
	v_sub_f32_e32 v124, v30, v35
	v_sub_f32_e32 v123, v29, v35
	v_sub_f32_e32 v122, v28, v35
	v_sub_f32_e32 v121, v27, v35
	v_sub_f32_e32 v120, v26, v35
	v_sub_f32_e32 v119, v25, v35
	v_sub_f32_e32 v118, v24, v35
	v_sub_f32_e32 v117, v23, v35
	v_sub_f32_e32 v116, v22, v35
	v_sub_f32_e32 v115, v21, v35
	v_sub_f32_e32 v114, v20, v35
	v_sub_f32_e32 v113, v19, v35
	v_sub_f32_e32 v112, v18, v35
	v_sub_f32_e32 v96, 4.0, v35
	v_mov_b32_e32 v2, v1
	v_mov_b32_e32 v3, v1
	v_mov_b32_e32 v4, v1
	v_mov_b32_e32 v5, v1
	v_mov_b32_e32 v6, v1
	v_mov_b32_e32 v7, v1
	v_mov_b32_e32 v8, v1
	v_mov_b32_e32 v9, v1
	v_mov_b32_e32 v10, v1
	v_mov_b32_e32 v11, v1
	v_mov_b32_e32 v12, v1
	v_mov_b32_e32 v13, v1
	v_mov_b64_e32 v[78:79], v[14:15]
	v_mov_b64_e32 v[62:63], v[14:15]
	v_mov_b64_e32 v[46:47], v[14:15]
	v_mov_b64_e32 v[30:31], v[14:15]
	v_mov_b64_e32 v[94:95], v[14:15]
	v_mov_b32_e32 v97, v96
	v_mov_b32_e32 v98, v96
	v_mov_b32_e32 v99, v96
	v_mov_b32_e32 v100, v96
	v_mov_b32_e32 v101, v96
	v_mov_b32_e32 v102, v96
	v_mov_b32_e32 v103, v96
	v_mov_b32_e32 v104, v96
	v_mov_b32_e32 v105, v96
	v_mov_b32_e32 v106, v96
	v_mov_b32_e32 v107, v96
	v_mov_b32_e32 v108, v96
	v_mov_b32_e32 v109, v96
	v_mov_b32_e32 v110, v96
	v_mov_b32_e32 v111, v96
	v_mov_b64_e32 v[76:77], v[12:13]
	v_mov_b64_e32 v[74:75], v[10:11]
	v_mov_b64_e32 v[72:73], v[8:9]
	v_mov_b64_e32 v[70:71], v[6:7]
	v_mov_b64_e32 v[68:69], v[4:5]
	v_mov_b64_e32 v[66:67], v[2:3]
	v_mov_b64_e32 v[64:65], v[0:1]
	v_mov_b64_e32 v[60:61], v[12:13]
	v_mov_b64_e32 v[58:59], v[10:11]
	v_mov_b64_e32 v[56:57], v[8:9]
	v_mov_b64_e32 v[54:55], v[6:7]
	v_mov_b64_e32 v[52:53], v[4:5]
	v_mov_b64_e32 v[50:51], v[2:3]
	v_mov_b64_e32 v[48:49], v[0:1]
	v_mov_b64_e32 v[44:45], v[12:13]
	v_mov_b64_e32 v[42:43], v[10:11]
	v_mov_b64_e32 v[40:41], v[8:9]
	v_mov_b64_e32 v[38:39], v[6:7]
	v_mov_b64_e32 v[36:37], v[4:5]
	v_mov_b64_e32 v[34:35], v[2:3]
	v_mov_b64_e32 v[32:33], v[0:1]
	v_mov_b64_e32 v[28:29], v[12:13]
	v_mov_b64_e32 v[26:27], v[10:11]
	v_mov_b64_e32 v[24:25], v[8:9]
	v_mov_b64_e32 v[22:23], v[6:7]
	v_mov_b64_e32 v[20:21], v[4:5]
	v_mov_b64_e32 v[18:19], v[2:3]
	v_mov_b64_e32 v[16:17], v[0:1]
	v_mov_b64_e32 v[92:93], v[12:13]
	v_mov_b64_e32 v[90:91], v[10:11]
	v_mov_b64_e32 v[88:89], v[8:9]
	v_mov_b64_e32 v[86:87], v[6:7]
	v_mov_b64_e32 v[84:85], v[4:5]
	v_mov_b64_e32 v[82:83], v[2:3]
	v_mov_b64_e32 v[80:81], v[0:1]
	v_lshlrev_b32_e32 v2, 4, v216
	v_and_b32_e32 v2, 0x3f0, v2
	v_or_b32_e32 v3, 0xffffe000, v2
	v_add_u32_e32 v4, s17, v3
	s_mov_b32 s0, 0xaaaaaaab
	v_mul_hi_u32 v5, v4, s0
	v_lshrrev_b32_e32 v6, 7, v5
	s_movk_i32 s0, 0xc0
	v_mul_lo_u32 v7, v6, s0
	v_add_u32_e32 v6, s22, v6
	s_movk_i32 s0, 0x300
	v_lshrrev_b32_e32 v5, 5, v5
	v_sub_u32_e32 v4, v4, v7
	v_mul_lo_u32 v6, v6, s0
	v_and_b32_e32 v5, 48, v5
	v_bitop3_b32 v4, v5, v6, v4 bitop3:0xde
	v_or_b32_e32 v8, s28, v2
	v_cndmask_b32_e64 v12, v8, v4, s[56:57]
	v_add_u32_e32 v4, s19, v3
	s_mov_b32 s0, 0xaaaaaaab
	v_mul_hi_u32 v5, v4, s0
	v_lshrrev_b32_e32 v6, 7, v5
	s_movk_i32 s0, 0xc0
	v_mul_lo_u32 v7, v6, s0
	v_add_u32_e32 v6, s34, v6
	s_movk_i32 s0, 0x300
	v_lshrrev_b32_e32 v5, 5, v5
	v_sub_u32_e32 v4, v4, v7
	v_mul_lo_u32 v6, v6, s0
	v_and_b32_e32 v5, 48, v5
	v_bitop3_b32 v4, v5, v6, v4 bitop3:0xde
	v_or_b32_e32 v8, s35, v2
	v_cndmask_b32_e64 v13, v4, v8, s[4:5]
	v_add_u32_e32 v4, s46, v3
	s_mov_b32 s0, 0xaaaaaaab
	v_mul_hi_u32 v5, v4, s0
	v_lshrrev_b32_e32 v6, 7, v5
	s_movk_i32 s0, 0xc0
	v_mul_lo_u32 v7, v6, s0
	v_add_u32_e32 v6, s3, v6
	s_movk_i32 s0, 0x300
	v_lshrrev_b32_e32 v5, 5, v5
	v_sub_u32_e32 v4, v4, v7
	v_mul_lo_u32 v6, v6, s0
	v_and_b32_e32 v5, 48, v5
	v_bitop3_b32 v4, v5, v6, v4 bitop3:0xde
	v_or_b32_e32 v8, s26, v2
	v_cndmask_b32_e64 v14, v4, v8, s[6:7]
	v_add_u32_e32 v4, s50, v3
	s_mov_b32 s0, 0xaaaaaaab
	v_mul_hi_u32 v5, v4, s0
	v_lshrrev_b32_e32 v6, 7, v5
	s_movk_i32 s0, 0xc0
	v_mul_lo_u32 v7, v6, s0
	v_add_u32_e32 v6, s30, v6
	s_movk_i32 s0, 0x300
	v_lshrrev_b32_e32 v5, 5, v5
	v_sub_u32_e32 v4, v4, v7
	v_mul_lo_u32 v6, v6, s0
	v_and_b32_e32 v5, 48, v5
	v_bitop3_b32 v4, v5, v6, v4 bitop3:0xde
	v_or_b32_e32 v8, s31, v2
	v_cndmask_b32_e64 v15, v4, v8, s[8:9]
	v_add_u32_e32 v4, s51, v3
	s_mov_b32 s0, 0xaaaaaaab
	v_mul_hi_u32 v5, v4, s0
	v_lshrrev_b32_e32 v6, 7, v5
	s_movk_i32 s0, 0xc0
	v_mul_lo_u32 v7, v6, s0
	v_add_u32_e32 v6, s16, v6
	s_movk_i32 s0, 0x300
	v_lshrrev_b32_e32 v5, 5, v5
	v_sub_u32_e32 v4, v4, v7
	v_mul_lo_u32 v6, v6, s0
	v_and_b32_e32 v5, 48, v5
	v_bitop3_b32 v4, v5, v6, v4 bitop3:0xde
	v_or_b32_e32 v8, s18, v2
	v_cndmask_b32_e64 v9, v4, v8, s[10:11]
	v_mov_b32_e32 v5, 0x19000
	v_lshl_add_u32 v6, v216, 4, v5
	v_lshl_add_u32 v7, v216, 2, v5
	ds_write_b128 v6, v[12:15]
	ds_write_b32 v7, v9 offset:8192
	s_bitcmp1_b32 s15, 0
	s_cselect_b32 s1, 0x6000, 0
	v_add_u32_e32 v12, s1, v244
	v_add_u32_e32 v13, s1, v245
	v_add_u32_e32 v14, 0xf000, v12
	v_add_u32_e32 v15, 0xf000, v13
	ds_read_b128 v[202:205], v12 offset:61440
	ds_read_b128 v[206:209], v13 offset:61440
	ds_read_b128 v[194:197], v14 offset:6144
	ds_read_b128 v[198:201], v15 offset:6144
	s_mov_b32 s82, 0xffff3000
	s_mov_b32 s83, 0xffff4000
	s_branch .LBB0_589

; #define LAS __attribute__((address_space(3)))
; #define SBAR() __builtin_amdgcn_sched_barrier(0)
; #define MFMA8(A, B, C) __builtin_amdgcn_mfma_scale_f32_32x32x64_f8f6f4(A, B, C, 0, 0, 0, 0x7F7F7F7F, 0, 0x7F7F7F7F)
; __device__ __forceinline__ v8i ld32(const LAS char* a0, const LAS char* a1) { const v4i x = *(const LAS v4i*)a0, y = *(const LAS v4i*)a1; return (v8i){x[0], x[1], x[2], x[3], y[0], y[1], y[2], y[3]}; }
; #define MFMA8QK(A, B, C) __builtin_amdgcn_mfma_scale_f32_32x32x64_f8f6f4(A, B, C, 0, 0, 0, 0x7F7F7F7F, 0, 0x7C7C7C7C)
; #define WBAR() do { asm volatile("s_waitcnt vmcnt(0) lgkmcnt(0)" ::: "memory"); __builtin_amdgcn_s_barrier(); asm volatile("" ::: "memory"); } while (0)
; __device__ __forceinline__ void qkt(f32x16& p0, f32x16& p1, const LAS char* Ks, int ka0, int ka1, const v8i* qf, const f32x16& negm) {
; #pragma unroll
;     for (int st = 0; st < 3; ++st) {
;         const v8i k0 = ld32(Ks + ka0 + 64 * st, Ks + ka1 + 64 * st), k1 = ld32(Ks + ka0 + 64 * st + 32 * 192, Ks + ka1 + 64 * st + 32 * 192);
;         if (st == 0) { p0 = MFMA8QK(k0, qf[st], negm); p1 = MFMA8QK(k1, qf[st], negm); }
;         else { p0 = MFMA8QK(k0, qf[st], p0); p1 = MFMA8QK(k1, qf[st], p1); } }
; }
; __device__ __forceinline__ void pv_d0(f32x16* o, const LAS char* Vs, int va0, int va1, v8i pa) {
; #pragma unroll
;     for (int d0 = 0; d0 < 4; ++d0) { const v8i vf = ld32(Vs + va0 + 2048 * d0, Vs + va1 + 2048 * d0); o[d0] = MFMA8(pa, vf, o[d0]); }
;     const v8i ones = {0x38383838, 0x38383838, 0x38383838, 0x38383838, 0x38383838, 0x38383838, 0x38383838, 0x38383838};
;     o[4] = MFMA8(pa, ones, o[4]);
; }
; __device__ __forceinline__ void attn_unit(const unsigned char* __restrict__ Qb, const unsigned char* __restrict__ Kh, const unsigned char* __restrict__ VTh, f16* __restrict__ Ob, int seq, LAS char* lds) {
;     ...
;     for (int j = 1; j + 1 < NT; j += 2) {
;         SBAR(); qkt(pB0, pB1, KSL(j), ka0, ka1, qf, negm);
;         finishSM(pA0, pA1, pa); SBAR();
;         pv_d0(o, VSL(j - 1), va0, va1, pa); partialSM<false>(pB0, pB1, negm, dlB, alB);
;         WBAR();
.LBB0_589:
	s_bitcmp1_b32 s15, 0
	s_cselect_b32 s0, 0x6000, 0
	s_add_i32 s0, s0, 0
	v_add_u32_e32 v0, s0, v244
	v_add_u32_e32 v210, s0, v245
	v_add_u32_e32 v211, 0xf000, v0
	v_add_u32_e32 v212, 0xf000, v210
	ds_read_b128 v[2:5], v0 offset:61504
	ds_read_b128 v[6:9], v210 offset:61504
	v_exp_f32_e32 v14, v116
	v_exp_f32_e32 v15, v117
	v_exp_f32_e32 v12, v114
	v_exp_f32_e32 v13, v115
	s_waitcnt lgkmcnt(4)
	v_mfma_scale_f32_32x32x64_f8f6f4 v[144:159], v[202:209], v[184:191], v[96:111], v234, v233 op_sel_hi:[0,0,0]
	ds_read_b128 v[202:205], v211 offset:6208
	ds_read_b128 v[206:209], v212 offset:6208
	v_exp_f32_e32 v114, v118
	v_exp_f32_e32 v115, v119
	v_exp_f32_e32 v119, v120
	v_exp_f32_e32 v120, v121
	v_cvt_pk_fp8_f32 v117, v14, v15
	v_exp_f32_e32 v10, v112
	v_exp_f32_e32 v11, v113
	s_waitcnt lgkmcnt(4)
	v_mfma_scale_f32_32x32x64_f8f6f4 v[128:143], v[194:201], v[184:191], v[96:111], v234, v233 op_sel_hi:[0,0,0]
	ds_read_b128 v[194:197], v0 offset:61568
	ds_read_b128 v[198:201], v210 offset:61568
	v_exp_f32_e32 v121, v122
	v_exp_f32_e32 v122, v123
	v_exp_f32_e32 v123, v124
	v_exp_f32_e32 v124, v125
	v_cvt_pk_fp8_f32 v117, v114, v115 op_sel:[0,0,1]
	v_cvt_pk_fp8_f32 v118, v119, v120
	v_exp_f32_e32 v125, v126
	s_waitcnt lgkmcnt(4)
	v_mfma_scale_f32_32x32x64_f8f6f4 v[144:159], v[2:9], v[176:183], v[144:159], v234, v233 op_sel_hi:[0,0,0]
	ds_read_b128 v[2:5], v211 offset:6272
	ds_read_b128 v[6:9], v212 offset:6272
	v_exp_f32_e32 v126, v127
	v_cvt_pk_fp8_f32 v112, v228, v229
	v_cvt_pk_fp8_f32 v116, v10, v11
	v_cvt_pk_fp8_f32 v113, v226, v227
	v_cvt_pk_fp8_f32 v114, v222, v223
	v_cvt_pk_fp8_f32 v115, v166, v167
	s_waitcnt lgkmcnt(4)
	v_mfma_scale_f32_32x32x64_f8f6f4 v[128:143], v[202:209], v[176:183], v[128:143], v234, v233 op_sel_hi:[0,0,0]
	v_cvt_pk_fp8_f32 v119, v123, v124
	v_cvt_pk_fp8_f32 v112, v220, v221 op_sel:[0,0,1]
	v_cvt_pk_fp8_f32 v116, v12, v13 op_sel:[0,0,1]
	v_cvt_pk_fp8_f32 v113, v224, v225 op_sel:[0,0,1]
	v_cvt_pk_fp8_f32 v114, v162, v163 op_sel:[0,0,1]
	v_cvt_pk_fp8_f32 v118, v121, v122 op_sel:[0,0,1]
	s_waitcnt lgkmcnt(2)
	v_mfma_scale_f32_32x32x64_f8f6f4 v[144:159], v[194:201], v[168:175], v[144:159], v234, v233 op_sel_hi:[0,0,0]
	v_cvt_pk_fp8_f32 v115, v164, v165 op_sel:[0,0,1]
	v_cvt_pk_fp8_f32 v119, v125, v126 op_sel:[0,0,1]
	v_mov_b32_e32 v161, v160
	v_mov_b32_e32 v162, v160
	v_mov_b32_e32 v163, v160
	s_waitcnt lgkmcnt(0)
	v_mfma_scale_f32_32x32x64_f8f6f4 v[128:143], v[2:9], v[168:175], v[128:143], v234, v233 op_sel_hi:[0,0,0]
	v_mov_b32_e32 v164, v160
	v_mov_b32_e32 v165, v160
	v_mov_b32_e32 v166, v160
	v_mov_b32_e32 v167, v160
	s_add_i32 s66, s21, -2
	s_ashr_i32 s38, s66, 1
	s_mul_hi_i32 s0, s38, 0x55555556
	s_lshr_b32 s1, s0, 31
	s_add_i32 s0, s0, s1
	s_mul_i32 s0, s0, 3
	s_sub_i32 s0, s38, s0
	s_lshl_b32 s0, s0, 14
	s_add_i32 s0, s0, 0
	v_add_u32_e32 v0, s0, v241
	v_add_u32_e32 v11, s0, v240
	ds_read_b128 v[208:211], v0
	ds_read_b128 v[212:215], v11
	ds_read_b128 v[200:203], v0 offset:2048
	ds_read_b128 v[204:207], v11 offset:2048
	ds_read_b128 v[192:195], v0 offset:4096
	ds_read_b128 v[196:199], v11 offset:4096
	ds_read_b128 v[2:5], v0 offset:6144
	ds_read_b128 v[6:9], v11 offset:6144
	v_mov_b32_e32 v125, 0x19000
	v_lshl_add_u32 v126, v216, 4, v125
	v_lshl_add_u32 v127, v216, 2, v125
	ds_read_b128 v[120:123], v126
	ds_read_b32 v124, v127 offset:8192
	v_max_f32_e32 v0, v145, v145
	v_max_f32_e32 v125, v144, v144
	v_max_f32_e32 v0, v125, v0
	v_max3_f32 v0, v0, v146, v147
	v_max3_f32 v0, v0, v148, v149
	v_max3_f32 v0, v0, v150, v151
	v_max3_f32 v0, v0, v152, v153
	v_max3_f32 v0, v0, v154, v155
	v_max3_f32 v0, v0, v156, v157
	v_max3_f32 v0, v0, v158, v159
	s_waitcnt lgkmcnt(8)
	v_mfma_scale_f32_32x32x64_f8f6f4 v[64:79], v[112:119], v[208:215], v[64:79], v234, v234 op_sel_hi:[0,0,0]
	v_exp_f32_e32 v14, v144
	v_exp_f32_e32 v15, v145
	v_exp_f32_e32 v10, v148
	v_exp_f32_e32 v11, v149
	v_max3_f32 v0, v0, v128, v129
	v_max3_f32 v0, v0, v130, v131
	v_max3_f32 v0, v0, v132, v133
	v_max3_f32 v0, v0, v134, v135
	s_waitcnt lgkmcnt(6)
	v_mfma_scale_f32_32x32x64_f8f6f4 v[48:63], v[112:119], v[200:207], v[48:63], v234, v234 op_sel_hi:[0,0,0]
	v_exp_f32_e32 v12, v150
	v_exp_f32_e32 v13, v151
	v_max3_f32 v0, v0, v136, v137
	v_max3_f32 v0, v0, v138, v139
	v_max3_f32 v0, v0, v140, v141
	v_max3_f32 v0, v0, v142, v143
	s_waitcnt lgkmcnt(4)
	v_mfma_scale_f32_32x32x64_f8f6f4 v[32:47], v[112:119], v[192:199], v[32:47], v234, v234 op_sel_hi:[0,0,0]
	v_exp_f32_e32 v192, v146
	v_exp_f32_e32 v193, v147
	v_mov_b32_e32 v125, v0
	s_nop 1
	v_permlane32_swap_b32_e32 v0, v125
	v_max_f32_e32 v125, v125, v125
	v_max_f32_e32 v0, v0, v0
	s_waitcnt lgkmcnt(2)
	v_mfma_scale_f32_32x32x64_f8f6f4 v[16:31], v[112:119], v[2:9], v[16:31], v234, v234 op_sel_hi:[0,0,0]
	v_exp_f32_e32 v6, v152
	v_exp_f32_e32 v7, v153
	v_exp_f32_e32 v8, v154
	v_exp_f32_e32 v9, v155
	v_exp_f32_e32 v2, v156
	v_exp_f32_e32 v3, v157
	v_exp_f32_e32 v4, v158
	v_exp_f32_e32 v5, v159
	v_mfma_scale_f32_32x32x64_f8f6f4 v[80:95], v[112:119], v[160:167], v[80:95], v234, v234 op_sel_hi:[0,0,0]
	s_waitcnt vmcnt(0) lgkmcnt(0)
	s_barrier
	v_max_f32_e32 v0, v0, v125
	s_add_i32 s42, s38, 2
	v_cmp_ge_f32_e64 s[0:1], s67, v0
	s_cmp_ge_i32 s42, s14
	s_cbranch_scc1 .Lattn_noissue
; #define WBAR() do { asm volatile("s_waitcnt vmcnt(0) lgkmcnt(0)" ::: "memory"); __builtin_amdgcn_s_barrier(); asm volatile("" ::: "memory"); } while (0)
; #define FIX(a, dlt, P0, P1) do { if (__any((dlt) > 0.f)) { if (hi == 0) al_l[r32] = (a); asm volatile("s_waitcnt lgkmcnt(0)" ::: "memory"); \
;     _Pragma("unroll") for (int d = 0; d < 5; ++d) _Pragma("unroll") for (int r = 0; r < 16; ++r) o[d][r] *= al_l[crow(r, hi)]; \
;     _Pragma("unroll") for (int r = 0; r < 16; ++r) { P0[r] *= (a); P1[r] -= (dlt); negm[r] -= (dlt); } } } while (0)
; __device__ __forceinline__ void attn_unit(const unsigned char* __restrict__ Qb, const unsigned char* __restrict__ Kh, const unsigned char* __restrict__ VTh, f16* __restrict__ Ob, int seq, LAS char* lds) {
;     ...
;         WBAR();
;         { const int J = (j - 1) >> 1; if (J + 2 < NS) ISSUE(J + 2); }
;         FIX(alB, dlB, pB0, pB1);
	s_bitcmp1_b32 s21, 1
	s_cselect_b32 s44, 0x6000, 0
	v_add_u32_e32 v126, s44, v244
	v_add_u32_e32 v127, s44, v245
	ds_read_b128 v[208:211], v126 offset:49152
	ds_read_b128 v[212:215], v127 offset:49152
	s_ashr_i32 s43, s42, 31
	s_mul_i32 s38, s42, 0x18000
	s_mul_hi_i32 s39, s42, 0x18000
	s_add_u32 s38, s24, s38
	s_addc_u32 s39, s25, s39
	s_lshl_b64 s[40:41], s[42:43], 14
	s_add_u32 s40, s52, s40
	s_addc_u32 s41, s53, s41
	s_mul_hi_i32 s43, s42, 0x55555556
	s_lshr_b32 s67, s43, 31
	s_add_i32 s43, s43, s67
	s_mul_i32 s43, s43, 3
	s_sub_i32 s42, s42, s43
	s_lshl_b32 s67, s42, 14
	s_bitcmp1_b32 s66, 1
	s_mov_b32 s42, 0xa000
	s_cselect_b32 s66, 0x10000, s42
	s_add_i32 s42, s67, s28
	s_add_i32 s43, s29, s66
	s_and_b64 vcc, s[54:55], exec
	s_cselect_b32 s42, s42, s43
	s_mov_b32 m0, s42
	s_and_b64 vcc, exec, s[56:57]
	s_cselect_b32 s44, s38, s40
	s_cselect_b32 s45, s39, s41
	global_load_lds_dwordx4 v120, s[44:45]
	s_add_i32 s42, s67, s35
	s_add_i32 s43, s2, s66
	s_and_b64 vcc, s[58:59], exec
	s_cselect_b32 s42, s42, s43
	s_mov_b32 m0, s42
	s_and_b64 vcc, exec, s[4:5]
	s_cselect_b32 s44, s40, s38
	s_cselect_b32 s45, s41, s39
	global_load_lds_dwordx4 v121, s[44:45]
	s_add_i32 s42, s67, s26
	s_add_i32 s43, s27, s66
	s_and_b64 vcc, s[60:61], exec
	s_cselect_b32 s42, s42, s43
	s_mov_b32 m0, s42
	s_and_b64 vcc, exec, s[6:7]
	s_cselect_b32 s44, s40, s38
	s_cselect_b32 s45, s41, s39
	global_load_lds_dwordx4 v122, s[44:45]
	s_add_i32 s42, s67, s31
	s_add_i32 s43, s49, s66
	s_and_b64 vcc, s[62:63], exec
	s_cselect_b32 s42, s42, s43
	s_mov_b32 m0, s42
	s_and_b64 vcc, exec, s[8:9]
	s_cselect_b32 s44, s40, s38
	s_cselect_b32 s45, s41, s39
	global_load_lds_dwordx4 v123, s[44:45]
	s_add_i32 s42, s67, s18
	s_add_i32 s43, s33, s66
	s_and_b64 vcc, s[64:65], exec
	s_cselect_b32 s42, s42, s43
	s_mov_b32 m0, s42
	s_and_b64 vcc, exec, s[10:11]
	s_cselect_b32 s44, s40, s38
	s_cselect_b32 s45, s41, s39
	global_load_lds_dwordx4 v124, s[44:45]
	s_mov_b32 s67, 0x41000000
	ds_read_b128 v[120:123], v126 offset:55296
	ds_read_b128 v[124:127], v127 offset:55296
	v_add_f32_e32 v0, -4.0, v0
	s_cmp_lg_u64 s[0:1], exec
	v_max_f32_e32 v0, 0, v0
	s_cselect_b64 vcc, -1, 0
	v_cndmask_b32_e32 v0, 0, v0, vcc
	v_cmp_lt_f32_e32 vcc, 0, v0
	s_cbranch_vccz .LBB0_615
	s_branch .Lattn_fix1
.Lattn_noissue:
	s_bitcmp1_b32 s21, 1
	s_cselect_b32 s44, 0x6000, 0
	v_add_u32_e32 v126, s44, v244
	v_add_u32_e32 v127, s44, v245
	ds_read_b128 v[208:211], v126 offset:49152
	ds_read_b128 v[212:215], v127 offset:49152
	ds_read_b128 v[120:123], v126 offset:55296
	ds_read_b128 v[124:127], v127 offset:55296
	v_add_f32_e32 v0, -4.0, v0
	s_cmp_lg_u64 s[0:1], exec
	v_max_f32_e32 v0, 0, v0
	s_cselect_b64 vcc, -1, 0
	v_cndmask_b32_e32 v0, 0, v0, vcc
	v_cmp_lt_f32_e32 vcc, 0, v0
	s_cbranch_vccz .LBB0_615
.Lattn_fix1:
	v_exp_f32_e64 v112, -v0
	s_and_saveexec_b64 s[0:1], s[12:13]
	ds_write_b32 v243, v112 offset:128
	s_or_b64 exec, exec, s[0:1]
	s_waitcnt lgkmcnt(0)
	v_add_u32_e32 v113, s20, v242
	ds_read_b128 v[114:117], v113 offset:224
	ds_read_b128 v[118:121], v113 offset:192
	ds_read_b128 v[122:125], v113 offset:160
	ds_read_b128 v[144:147], v113 offset:128
	v_pk_add_f32 v[128:129], v[128:129], v[0:1] op_sel_hi:[1,0] neg_lo:[0,1] neg_hi:[0,1]
	s_waitcnt lgkmcnt(0)
	v_pk_mul_f32 v[76:77], v[76:77], v[114:115]
	v_pk_mul_f32 v[72:73], v[72:73], v[118:119]
	v_pk_mul_f32 v[68:69], v[68:69], v[122:123]
	v_pk_mul_f32 v[78:79], v[78:79], v[116:117]
	v_pk_mul_f32 v[74:75], v[74:75], v[120:121]
	v_pk_mul_f32 v[70:71], v[70:71], v[124:125]
	v_pk_mul_f32 v[66:67], v[66:67], v[146:147]
	v_pk_mul_f32 v[64:65], v[64:65], v[144:145]
	v_pk_mul_f32 v[60:61], v[60:61], v[114:115]
	v_pk_mul_f32 v[56:57], v[56:57], v[118:119]
	v_pk_mul_f32 v[52:53], v[52:53], v[122:123]
	v_pk_mul_f32 v[62:63], v[62:63], v[116:117]
	v_pk_mul_f32 v[58:59], v[58:59], v[120:121]
	v_pk_mul_f32 v[54:55], v[54:55], v[124:125]
	v_pk_mul_f32 v[50:51], v[50:51], v[146:147]
	v_pk_mul_f32 v[48:49], v[48:49], v[144:145]
	v_pk_mul_f32 v[44:45], v[44:45], v[114:115]
	v_pk_mul_f32 v[40:41], v[40:41], v[118:119]
	v_pk_mul_f32 v[36:37], v[36:37], v[122:123]
	v_pk_mul_f32 v[46:47], v[46:47], v[116:117]
	v_pk_mul_f32 v[42:43], v[42:43], v[120:121]
	v_pk_mul_f32 v[38:39], v[38:39], v[124:125]
	v_pk_mul_f32 v[34:35], v[34:35], v[146:147]
	v_pk_mul_f32 v[32:33], v[32:33], v[144:145]
	v_pk_mul_f32 v[28:29], v[28:29], v[114:115]
	v_pk_mul_f32 v[24:25], v[24:25], v[118:119]
	v_pk_mul_f32 v[20:21], v[20:21], v[122:123]
	v_pk_mul_f32 v[30:31], v[30:31], v[116:117]
	v_pk_mul_f32 v[26:27], v[26:27], v[120:121]
	v_pk_mul_f32 v[22:23], v[22:23], v[124:125]
	v_pk_mul_f32 v[18:19], v[18:19], v[146:147]
	v_pk_mul_f32 v[16:17], v[16:17], v[144:145]
	v_pk_mul_f32 v[92:93], v[92:93], v[114:115]
	v_pk_mul_f32 v[88:89], v[88:89], v[118:119]
	v_pk_mul_f32 v[84:85], v[84:85], v[122:123]
	v_pk_mul_f32 v[94:95], v[94:95], v[116:117]
	v_pk_mul_f32 v[90:91], v[90:91], v[120:121]
	v_pk_mul_f32 v[86:87], v[86:87], v[124:125]
	v_pk_mul_f32 v[82:83], v[82:83], v[146:147]
	v_pk_mul_f32 v[80:81], v[80:81], v[144:145]
	v_pk_add_f32 v[130:131], v[130:131], v[0:1] op_sel_hi:[1,0] neg_lo:[0,1] neg_hi:[0,1]
	v_pk_add_f32 v[132:133], v[132:133], v[0:1] op_sel_hi:[1,0] neg_lo:[0,1] neg_hi:[0,1]
	v_pk_add_f32 v[134:135], v[134:135], v[0:1] op_sel_hi:[1,0] neg_lo:[0,1] neg_hi:[0,1]
	v_pk_add_f32 v[136:137], v[136:137], v[0:1] op_sel_hi:[1,0] neg_lo:[0,1] neg_hi:[0,1]
	v_pk_add_f32 v[138:139], v[138:139], v[0:1] op_sel_hi:[1,0] neg_lo:[0,1] neg_hi:[0,1]
	v_pk_add_f32 v[140:141], v[140:141], v[0:1] op_sel_hi:[1,0] neg_lo:[0,1] neg_hi:[0,1]
	v_pk_mul_f32 v[4:5], v[4:5], v[112:113] op_sel_hi:[1,0]
	v_pk_mul_f32 v[2:3], v[2:3], v[112:113] op_sel_hi:[1,0]
	v_pk_mul_f32 v[8:9], v[8:9], v[112:113] op_sel_hi:[1,0]
	v_pk_mul_f32 v[6:7], v[6:7], v[112:113] op_sel_hi:[1,0]
	v_pk_mul_f32 v[12:13], v[12:13], v[112:113] op_sel_hi:[1,0]
	v_pk_mul_f32 v[10:11], v[10:11], v[112:113] op_sel_hi:[1,0]
	v_pk_mul_f32 v[192:193], v[192:193], v[112:113] op_sel_hi:[1,0]
	v_pk_mul_f32 v[14:15], v[14:15], v[112:113] op_sel_hi:[1,0]
	v_pk_add_f32 v[142:143], v[142:143], v[0:1] op_sel_hi:[1,0] neg_lo:[0,1] neg_hi:[0,1]
	v_sub_f32_e32 v111, v111, v0
	v_sub_f32_e32 v110, v110, v0
	v_sub_f32_e32 v109, v109, v0
	v_sub_f32_e32 v108, v108, v0
	v_sub_f32_e32 v107, v107, v0
	v_sub_f32_e32 v106, v106, v0
	v_sub_f32_e32 v105, v105, v0
	v_sub_f32_e32 v104, v104, v0
	v_sub_f32_e32 v103, v103, v0
	v_sub_f32_e32 v102, v102, v0
	v_sub_f32_e32 v101, v101, v0
	v_sub_f32_e32 v100, v100, v0
	v_sub_f32_e32 v99, v99, v0
	v_sub_f32_e32 v98, v98, v0
	v_sub_f32_e32 v97, v97, v0
	v_sub_f32_e32 v96, v96, v0
	s_bitcmp1_b32 s21, 1
	s_cselect_b32 s0, 0x6000, 0
	v_add_u32_e32 v126, s0, v244
	v_add_u32_e32 v127, s0, v245
	ds_read_b128 v[120:123], v126 offset:55296
	ds_read_b128 v[124:127], v127 offset:55296
; #define LAS __attribute__((address_space(3)))
; __device__ __forceinline__ unsigned pk4_fp8(float a, float b, float c, float d) { int w = 0; w = __builtin_amdgcn_cvt_pk_fp8_f32(a, b, w, false); w = __builtin_amdgcn_cvt_pk_fp8_f32(c, d, w, true); return (unsigned)w; }
; #define SBAR() __builtin_amdgcn_sched_barrier(0)
; #define MFMA8(A, B, C) __builtin_amdgcn_mfma_scale_f32_32x32x64_f8f6f4(A, B, C, 0, 0, 0, 0x7F7F7F7F, 0, 0x7F7F7F7F)
; __device__ __forceinline__ void finishSM(f32x16& p0, f32x16& p1, v8i& pa) {
; #pragma unroll
;     for (int r = 0; r < 16; ++r) p1[r] = __builtin_amdgcn_exp2f(p1[r]);
; #pragma unroll
;     for (int w = 0; w < 4; ++w) { pa[w] = (int)pk4_fp8(p0[4 * w], p0[4 * w + 1], p0[4 * w + 2], p0[4 * w + 3]); pa[4 + w] = (int)pk4_fp8(p1[4 * w], p1[4 * w + 1], p1[4 * w + 2], p1[4 * w + 3]); }
; }
; __device__ __forceinline__ v8i ld32(const LAS char* a0, const LAS char* a1) { const v4i x = *(const LAS v4i*)a0, y = *(const LAS v4i*)a1; return (v8i){x[0], x[1], x[2], x[3], y[0], y[1], y[2], y[3]}; }
; __device__ __forceinline__ void qkt(f32x16& p0, f32x16& p1, const LAS char* Ks, int ka0, int ka1, const v8i* qf, const f32x16& negm) {
; #pragma unroll
;     for (int st = 0; st < 3; ++st) {
;         const v8i k0 = ld32(Ks + ka0 + 64 * st, Ks + ka1 + 64 * st), k1 = ld32(Ks + ka0 + 64 * st + 32 * 192, Ks + ka1 + 64 * st + 32 * 192);
;         if (st == 0) { p0 = MFMA8QK(k0, qf[st], negm); p1 = MFMA8QK(k1, qf[st], negm); }
;         else { p0 = MFMA8QK(k0, qf[st], p0); p1 = MFMA8QK(k1, qf[st], p1); } }
; }
; __device__ __forceinline__ void pv_d0(f32x16* o, const LAS char* Vs, int va0, int va1, v8i pa) {
; #pragma unroll
;     for (int d0 = 0; d0 < 4; ++d0) { const v8i vf = ld32(Vs + va0 + 2048 * d0, Vs + va1 + 2048 * d0); o[d0] = MFMA8(pa, vf, o[d0]); }
;     const v8i ones = {0x38383838, 0x38383838, 0x38383838, 0x38383838, 0x38383838, 0x38383838, 0x38383838, 0x38383838};
;     o[4] = MFMA8(pa, ones, o[4]);
; }
; __device__ __forceinline__ void attn_unit(const unsigned char* __restrict__ Qb, const unsigned char* __restrict__ Kh, const unsigned char* __restrict__ VTh, f16* __restrict__ Ob, int seq, LAS char* lds) {
;     ...
;         SBAR(); qkt(pA0, pA1, KSL(j + 1), ka0, ka1, qf, negm);
;         finishSM(pB0, pB1, pa); SBAR();
;         pv_d0(o, VSL(j), va0, va1, pa); partialSM<false>(pA0, pA1, negm, dlA, alA);
;         FIX(alA, dlA, pA0, pA1);
.LBB0_615:
	s_mul_hi_u32 s0, s15, 0xaaaaaaab
	s_lshr_b32 s0, s0, 1
	s_mul_i32 s0, s0, 0xffff4000
	s_bfe_i32 s1, s21, 0x10001
	s_and_b32 s1, s1, 0x6000
	s_add_i32 s1, s1, 0
	v_add_u32_e32 v0, s1, v244
	v_add_u32_e32 v161, s1, v245
	ds_read_b128 v[194:197], v0 offset:55360
	ds_read_b128 v[198:201], v161 offset:55360
	v_exp_f32_e32 v129, v129
	v_exp_f32_e32 v162, v133
	s_waitcnt lgkmcnt(4)
	v_mfma_scale_f32_32x32x64_f8f6f4 v[144:159], v[208:215], v[184:191], v[96:111], v234, v233 op_sel_hi:[0,0,0]
	ds_read_b128 v[202:205], v0 offset:49216
	ds_read_b128 v[206:209], v161 offset:49216
	v_exp_f32_e32 v130, v130
	v_exp_f32_e32 v131, v131
	v_exp_f32_e32 v134, v134
	v_exp_f32_e32 v135, v135
	v_exp_f32_e32 v136, v136
	v_exp_f32_e32 v137, v137
	v_exp_f32_e32 v140, v140
	v_exp_f32_e32 v141, v141
	v_exp_f32_e32 v138, v138
	v_exp_f32_e32 v139, v139
	v_exp_f32_e32 v142, v142
	v_exp_f32_e32 v143, v143
	s_waitcnt lgkmcnt(4)
	v_mfma_scale_f32_32x32x64_f8f6f4 v[112:127], v[120:127], v[184:191], v[96:111], v234, v233 op_sel_hi:[0,0,0]
	s_waitcnt lgkmcnt(2)
	v_mfma_scale_f32_32x32x64_f8f6f4 v[112:127], v[194:201], v[176:183], v[112:127], v234, v233 op_sel_hi:[0,0,0]
	s_waitcnt lgkmcnt(0)
	v_mfma_scale_f32_32x32x64_f8f6f4 v[144:159], v[202:209], v[176:183], v[144:159], v234, v233 op_sel_hi:[0,0,0]
	ds_read_b128 v[194:197], v0 offset:55424
	ds_read_b128 v[198:201], v161 offset:55424
	ds_read_b128 v[202:205], v0 offset:49280
	ds_read_b128 v[206:209], v161 offset:49280
	v_exp_f32_e32 v0, v128
	v_exp_f32_e32 v161, v132
	v_cvt_pk_fp8_f32 v132, v0, v129
	v_cvt_pk_fp8_f32 v133, v161, v162
	v_cvt_pk_fp8_f32 v128, v14, v15
	v_cvt_pk_fp8_f32 v132, v130, v131 op_sel:[0,0,1]
	v_cvt_pk_fp8_f32 v133, v134, v135 op_sel:[0,0,1]
	s_waitcnt lgkmcnt(0)
	v_mfma_scale_f32_32x32x64_f8f6f4 v[112:127], v[194:201], v[168:175], v[112:127], v234, v233 op_sel_hi:[0,0,0]
	v_cvt_pk_fp8_f32 v129, v10, v11
	v_cvt_pk_fp8_f32 v130, v6, v7
	v_cvt_pk_fp8_f32 v134, v136, v137
	v_cvt_pk_fp8_f32 v131, v2, v3
	v_cvt_pk_fp8_f32 v135, v140, v141
	v_cvt_pk_fp8_f32 v128, v192, v193 op_sel:[0,0,1]
	v_cvt_pk_fp8_f32 v129, v12, v13 op_sel:[0,0,1]
	v_cvt_pk_fp8_f32 v130, v8, v9 op_sel:[0,0,1]
	v_cvt_pk_fp8_f32 v134, v138, v139 op_sel:[0,0,1]
	v_cvt_pk_fp8_f32 v131, v4, v5 op_sel:[0,0,1]
	v_cvt_pk_fp8_f32 v135, v142, v143 op_sel:[0,0,1]
	v_or_b32_e32 v10, s0, v218
	v_or_b32_e32 v11, s0, v250
	v_add_u32_e32 v10, v247, v10
	v_add_u32_e32 v11, v247, v11
	ds_read_b128 v[2:5], v10
	ds_read_b128 v[6:9], v11
	v_mfma_scale_f32_32x32x64_f8f6f4 v[144:159], v[202:209], v[168:175], v[144:159], v234, v233 op_sel_hi:[0,0,0]
	ds_read_b128 v[194:197], v10 offset:2048
	ds_read_b128 v[198:201], v11 offset:2048
	v_mov_b32_e32 v161, v160
	v_mov_b32_e32 v162, v160
	v_mov_b32_e32 v163, v160
	v_mov_b32_e32 v164, v160
	v_mov_b32_e32 v165, v160
	v_mov_b32_e32 v166, v160
	v_mov_b32_e32 v167, v160
	s_waitcnt lgkmcnt(2)
	v_mfma_scale_f32_32x32x64_f8f6f4 v[64:79], v[128:135], v[2:9], v[64:79], v234, v234 op_sel_hi:[0,0,0]
	ds_read_b128 v[2:5], v10 offset:4096
	ds_read_b128 v[6:9], v11 offset:4096
	s_waitcnt lgkmcnt(2)
	v_mfma_scale_f32_32x32x64_f8f6f4 v[48:63], v[128:135], v[194:201], v[48:63], v234, v234 op_sel_hi:[0,0,0]
	ds_read_b128 v[194:197], v10 offset:6144
	ds_read_b128 v[198:201], v11 offset:6144
	s_nop 2
	v_exp_f32_e32 v228, v144
	v_exp_f32_e32 v229, v145
	v_exp_f32_e32 v220, v146
	v_exp_f32_e32 v221, v147
	v_exp_f32_e32 v226, v148
	v_exp_f32_e32 v227, v149
	v_exp_f32_e32 v224, v150
	v_exp_f32_e32 v225, v151
	v_exp_f32_e32 v222, v152
	v_exp_f32_e32 v223, v153
	v_max_f32_e32 v0, v145, v145
	s_waitcnt lgkmcnt(2)
	v_mfma_scale_f32_32x32x64_f8f6f4 v[32:47], v[128:135], v[2:9], v[32:47], v234, v234 op_sel_hi:[0,0,0]
	v_max_f32_e32 v2, v144, v144
	v_max_f32_e32 v0, v2, v0
	v_max3_f32 v0, v0, v146, v147
	v_max3_f32 v0, v0, v148, v149
	v_max3_f32 v0, v0, v150, v151
	v_max3_f32 v0, v0, v152, v153
	v_max3_f32 v0, v0, v154, v155
	v_max3_f32 v0, v0, v156, v157
	v_max3_f32 v0, v0, v158, v159
	s_waitcnt lgkmcnt(0)
	v_mfma_scale_f32_32x32x64_f8f6f4 v[16:31], v[128:135], v[194:201], v[16:31], v234, v234 op_sel_hi:[0,0,0]
	s_bitcmp0_b32 s15, 0
	s_cselect_b32 s1, 0x6000, 0
	v_add_u32_e32 v12, s1, v244
	v_add_u32_e32 v13, s1, v245
	v_add_u32_e32 v14, 0xf000, v12
	v_add_u32_e32 v15, 0xf000, v13
	ds_read_b128 v[202:205], v12 offset:61440
	ds_read_b128 v[206:209], v13 offset:61440
	ds_read_b128 v[194:197], v14 offset:6144
	ds_read_b128 v[198:201], v15 offset:6144
	v_max3_f32 v0, v0, v112, v113
	v_max3_f32 v0, v0, v114, v115
	v_max3_f32 v0, v0, v116, v117
	v_max3_f32 v0, v0, v118, v119
	v_max3_f32 v0, v0, v120, v121
	v_max3_f32 v0, v0, v122, v123
	v_mfma_scale_f32_32x32x64_f8f6f4 v[80:95], v[128:135], v[160:167], v[80:95], v234, v234 op_sel_hi:[0,0,0]
	v_max3_f32 v0, v0, v124, v125
	v_max3_f32 v0, v0, v126, v127
	v_mov_b32_e32 v2, v0
	s_nop 1
	v_permlane32_swap_b32_e32 v0, v2
	v_max_f32_e32 v2, v2, v2
	v_max_f32_e32 v0, v0, v0
	v_max_f32_e32 v0, v0, v2
	v_cmp_ge_f32_e32 vcc, s67, v0
	v_add_f32_e32 v0, -4.0, v0
	s_cmp_lg_u64 vcc, exec
	v_exp_f32_e32 v162, v154
	v_exp_f32_e32 v163, v155
	v_exp_f32_e32 v166, v156
	v_exp_f32_e32 v167, v157
	v_exp_f32_e32 v164, v158
	v_exp_f32_e32 v165, v159
	v_max_f32_e32 v0, 0, v0
	s_cselect_b64 vcc, -1, 0
	v_cndmask_b32_e32 v2, 0, v0, vcc
	v_cmp_lt_f32_e32 vcc, 0, v2
	s_cbranch_vccz .LBB0_588
	v_exp_f32_e64 v0, -v2
	s_and_saveexec_b64 s[0:1], s[12:13]
	s_cbranch_execz .LBB0_587
	ds_write_b32 v243, v0 offset:128
	s_branch .LBB0_587
